# MLP-up GEMM epilogue: hand-generated straight-line relu^2 path (fewer address ops)
# baseline (speedup 1.0000x reference)
; __device__ __forceinline__ unsigned cvt_pk_bf16(float lo, float hi) { unsigned r; asm volatile("v_cvt_pk_bf16_f32 %0, %1, %2" : "=v"(r) : "v"(lo), "v"(hi)); return r; }
;     __device__ __forceinline__ void operator()(const f32x4 (&acc)[2][2][4][2], const Unit& u, int wr, int wc, int fr, int fq, int ui, PG8_LAS unsigned char* lds) const {
;     ...
;             for (int m = 0; m < 4; ++m) {
;                 if ((m & 1) == 0) {
;                     if (use_tab) { rs4[m] = tab[ai * HALF + m * 16] * sc; rs4[m + 1] = tab[ai * HALF + (m + 1) * 16] * sc; }
;                     else {
;                         asm volatile("" ::: "memory");
;                         rs4[m] = __builtin_amdgcn_rsqf(ssq_row(ssq, row0 + ai * HALF + m * 16) * (1.0f / 1024.0f) + RMS_EPS) * sc;
;                         rs4[m + 1] = __builtin_amdgcn_rsqf(ssq_row(ssq, row0 + ai * HALF + (m + 1) * 16) * (1.0f / 1024.0f) + RMS_EPS) * sc;
;                     }
;                 }
;                 const int row = row0 + ai * HALF + m * 16;
;                 const float rs = rs4[m];
;                 bf16_t* rowp = O + (size_t)row * ldc + col0;
; #pragma unroll
;                 for (int bj = 0; bj < 2; ++bj) {
;                     f32x4 v[2] = {acc[ai][bj][m][0] * rs, acc[ai][bj][m][1] * rs};
;                     if (ksum) { csum[bj][0] += v[0]; csum[bj][1] += v[1]; }
; #pragma unroll
;                     for (int n = 0; n < 2; ++n) {
;                         f32x4 lbv = (f32x4){0.f, 0.f, 0.f, 0.f};
;                         if (act == 2) lbv = *(const f32x4*)(lb + (col0 - 1024) + bj * HALF + 4 * n);
; #pragma unroll
;                         for (int e = 0; e < 4; ++e) {
;                             float x = v[n][e];
;                             if (act == 1) x = silu_f(x);
;                             else if (act == 2) { const float l = lbv[e]; x = __logf(l + (1.f - l) * __builtin_amdgcn_rcpf(1.f + __expf(-x))); }
;                             else if (act == 3) { x = fmaxf(x, 0.f); x = x * x; }
;                             v[n][e] = x;
;                         }
;                     }
;                     u32x4 w; w.x = cvt_pk_bf16(v[0][0], v[0][1]); w.y = cvt_pk_bf16(v[0][2], v[0][3]); w.z = cvt_pk_bf16(v[1][0], v[1][1]); w.w = cvt_pk_bf16(v[1][2], v[1][3]);
;                     *(u32x4*)(rowp + bj * HALF) = w;
.LBB0_1755:
	s_andn2_b64 vcc, exec, s[40:41]
	s_cbranch_vccnz .Lepi3_generic
	v_lshl_add_u32 v140, s67, 8, v146
	s_lshl_b32 s38, s68, 10
	v_add_u32_e32 v151, s38, v148
	ds_read_b32 v152, v151
	ds_read_b32 v154, v151 offset:64
	ds_read_b32 v156, v151 offset:128
	ds_read_b32 v158, v151 offset:192
	ds_read_b32 v160, v151 offset:512
	ds_read_b32 v162, v151 offset:576
	ds_read_b32 v164, v151 offset:640
	ds_read_b32 v166, v151 offset:704
	v_lshl_or_b32 v138, s65, 8, v149
	v_mov_b32_e32 v139, 0
	v_lshlrev_b32_e32 v142, 13, v140
	v_mov_b32_e32 v143, 0
	s_mov_b32 s0, 0x20000
	s_mov_b32 s1, 0
	s_mov_b32 s38, 0x100000
	s_mov_b32 s39, 0
	v_lshl_add_u64 v[142:143], v[142:143], 0, s[14:15]
	v_lshl_add_u64 v[142:143], v[138:139], 1, v[142:143]
	v_lshl_add_u64 v[168:169], v[142:143], 0, s[38:39]
	s_waitcnt lgkmcnt(0)
	v_pk_mul_f32 v[124:125], v[124:125], v[152:153] op_sel_hi:[1,0]
	v_pk_mul_f32 v[126:127], v[126:127], v[152:153] op_sel_hi:[1,0]
	v_pk_mul_f32 v[120:121], v[120:121], v[152:153] op_sel_hi:[1,0]
	v_pk_mul_f32 v[122:123], v[122:123], v[152:153] op_sel_hi:[1,0]
	v_max_f32_e32 v124, 0, v124
	v_max_f32_e32 v125, 0, v125
	v_max_f32_e32 v126, 0, v126
	v_max_f32_e32 v127, 0, v127
	v_max_f32_e32 v120, 0, v120
	v_max_f32_e32 v121, 0, v121
	v_max_f32_e32 v122, 0, v122
	v_max_f32_e32 v123, 0, v123
	v_pk_mul_f32 v[124:125], v[124:125], v[124:125]
	v_pk_mul_f32 v[126:127], v[126:127], v[126:127]
	v_pk_mul_f32 v[120:121], v[120:121], v[120:121]
	v_pk_mul_f32 v[122:123], v[122:123], v[122:123]
	v_cvt_pk_bf16_f32 v124, v124, v125
	v_cvt_pk_bf16_f32 v125, v126, v127
	v_cvt_pk_bf16_f32 v126, v120, v121
	v_cvt_pk_bf16_f32 v127, v122, v123
	global_store_dwordx4 v[142:143], v[124:127], off
	v_pk_mul_f32 v[116:117], v[116:117], v[152:153] op_sel_hi:[1,0]
	v_pk_mul_f32 v[118:119], v[118:119], v[152:153] op_sel_hi:[1,0]
	v_pk_mul_f32 v[112:113], v[112:113], v[152:153] op_sel_hi:[1,0]
	v_pk_mul_f32 v[114:115], v[114:115], v[152:153] op_sel_hi:[1,0]
	v_max_f32_e32 v116, 0, v116
	v_max_f32_e32 v117, 0, v117
	v_max_f32_e32 v118, 0, v118
	v_max_f32_e32 v119, 0, v119
	v_max_f32_e32 v112, 0, v112
	v_max_f32_e32 v113, 0, v113
	v_max_f32_e32 v114, 0, v114
	v_max_f32_e32 v115, 0, v115
	v_pk_mul_f32 v[116:117], v[116:117], v[116:117]
	v_pk_mul_f32 v[118:119], v[118:119], v[118:119]
	v_pk_mul_f32 v[112:113], v[112:113], v[112:113]
	v_pk_mul_f32 v[114:115], v[114:115], v[114:115]
	v_cvt_pk_bf16_f32 v116, v116, v117
	v_cvt_pk_bf16_f32 v117, v118, v119
	v_cvt_pk_bf16_f32 v118, v112, v113
	v_cvt_pk_bf16_f32 v119, v114, v115
	global_store_dwordx4 v[142:143], v[116:119], off offset:256
	v_lshl_add_u64 v[144:145], v[142:143], 0, s[0:1]
	v_pk_mul_f32 v[108:109], v[108:109], v[154:155] op_sel_hi:[1,0]
	v_pk_mul_f32 v[110:111], v[110:111], v[154:155] op_sel_hi:[1,0]
	v_pk_mul_f32 v[104:105], v[104:105], v[154:155] op_sel_hi:[1,0]
	v_pk_mul_f32 v[106:107], v[106:107], v[154:155] op_sel_hi:[1,0]
	v_max_f32_e32 v108, 0, v108
	v_max_f32_e32 v109, 0, v109
	v_max_f32_e32 v110, 0, v110
	v_max_f32_e32 v111, 0, v111
	v_max_f32_e32 v104, 0, v104
	v_max_f32_e32 v105, 0, v105
	v_max_f32_e32 v106, 0, v106
	v_max_f32_e32 v107, 0, v107
	v_pk_mul_f32 v[108:109], v[108:109], v[108:109]
	v_pk_mul_f32 v[110:111], v[110:111], v[110:111]
	v_pk_mul_f32 v[104:105], v[104:105], v[104:105]
	v_pk_mul_f32 v[106:107], v[106:107], v[106:107]
	v_cvt_pk_bf16_f32 v108, v108, v109
	v_cvt_pk_bf16_f32 v109, v110, v111
	v_cvt_pk_bf16_f32 v110, v104, v105
	v_cvt_pk_bf16_f32 v111, v106, v107
	global_store_dwordx4 v[144:145], v[108:111], off
	v_pk_mul_f32 v[100:101], v[100:101], v[154:155] op_sel_hi:[1,0]
	v_pk_mul_f32 v[102:103], v[102:103], v[154:155] op_sel_hi:[1,0]
	v_pk_mul_f32 v[96:97], v[96:97], v[154:155] op_sel_hi:[1,0]
	v_pk_mul_f32 v[98:99], v[98:99], v[154:155] op_sel_hi:[1,0]
	v_max_f32_e32 v100, 0, v100
	v_max_f32_e32 v101, 0, v101
	v_max_f32_e32 v102, 0, v102
	v_max_f32_e32 v103, 0, v103
	v_max_f32_e32 v96, 0, v96
	v_max_f32_e32 v97, 0, v97
	v_max_f32_e32 v98, 0, v98
	v_max_f32_e32 v99, 0, v99
	v_pk_mul_f32 v[100:101], v[100:101], v[100:101]
	v_pk_mul_f32 v[102:103], v[102:103], v[102:103]
	v_pk_mul_f32 v[96:97], v[96:97], v[96:97]
	v_pk_mul_f32 v[98:99], v[98:99], v[98:99]
	v_cvt_pk_bf16_f32 v100, v100, v101
	v_cvt_pk_bf16_f32 v101, v102, v103
	v_cvt_pk_bf16_f32 v102, v96, v97
	v_cvt_pk_bf16_f32 v103, v98, v99
	global_store_dwordx4 v[144:145], v[100:103], off offset:256
	v_lshl_add_u64 v[142:143], v[144:145], 0, s[0:1]
	v_pk_mul_f32 v[92:93], v[92:93], v[156:157] op_sel_hi:[1,0]
	v_pk_mul_f32 v[94:95], v[94:95], v[156:157] op_sel_hi:[1,0]
	v_pk_mul_f32 v[88:89], v[88:89], v[156:157] op_sel_hi:[1,0]
	v_pk_mul_f32 v[90:91], v[90:91], v[156:157] op_sel_hi:[1,0]
	v_max_f32_e32 v92, 0, v92
	v_max_f32_e32 v93, 0, v93
	v_max_f32_e32 v94, 0, v94
	v_max_f32_e32 v95, 0, v95
	v_max_f32_e32 v88, 0, v88
	v_max_f32_e32 v89, 0, v89
	v_max_f32_e32 v90, 0, v90
	v_max_f32_e32 v91, 0, v91
	v_pk_mul_f32 v[92:93], v[92:93], v[92:93]
	v_pk_mul_f32 v[94:95], v[94:95], v[94:95]
	v_pk_mul_f32 v[88:89], v[88:89], v[88:89]
	v_pk_mul_f32 v[90:91], v[90:91], v[90:91]
	v_cvt_pk_bf16_f32 v92, v92, v93
	v_cvt_pk_bf16_f32 v93, v94, v95
	v_cvt_pk_bf16_f32 v94, v88, v89
	v_cvt_pk_bf16_f32 v95, v90, v91
	global_store_dwordx4 v[142:143], v[92:95], off
	v_pk_mul_f32 v[84:85], v[84:85], v[156:157] op_sel_hi:[1,0]
	v_pk_mul_f32 v[86:87], v[86:87], v[156:157] op_sel_hi:[1,0]
	v_pk_mul_f32 v[80:81], v[80:81], v[156:157] op_sel_hi:[1,0]
	v_pk_mul_f32 v[82:83], v[82:83], v[156:157] op_sel_hi:[1,0]
	v_max_f32_e32 v84, 0, v84
	v_max_f32_e32 v85, 0, v85
	v_max_f32_e32 v86, 0, v86
	v_max_f32_e32 v87, 0, v87
	v_max_f32_e32 v80, 0, v80
	v_max_f32_e32 v81, 0, v81
; __device__ __forceinline__ unsigned cvt_pk_bf16(float lo, float hi) { unsigned r; asm volatile("v_cvt_pk_bf16_f32 %0, %1, %2" : "=v"(r) : "v"(lo), "v"(hi)); return r; }
; __device__ __forceinline__ float silu_f(float v) { return v * __builtin_amdgcn_rcpf(1.f + __expf(-v)); }
;     __device__ __forceinline__ void operator()(const f32x4 (&acc)[2][2][4][2], const Unit& u, int wr, int wc, int fr, int fq, int ui, PG8_LAS unsigned char* lds) const {
;     ...
;                     f32x4 v[2] = {acc[ai][bj][m][0] * rs, acc[ai][bj][m][1] * rs};
;                     if (ksum) { csum[bj][0] += v[0]; csum[bj][1] += v[1]; }
; #pragma unroll
;                     for (int n = 0; n < 2; ++n) {
;                         f32x4 lbv = (f32x4){0.f, 0.f, 0.f, 0.f};
;                         if (act == 2) lbv = *(const f32x4*)(lb + (col0 - 1024) + bj * HALF + 4 * n);
; #pragma unroll
;                         for (int e = 0; e < 4; ++e) {
;                             float x = v[n][e];
;                             if (act == 1) x = silu_f(x);
;                             else if (act == 2) { const float l = lbv[e]; x = __logf(l + (1.f - l) * __builtin_amdgcn_rcpf(1.f + __expf(-x))); }
;                             else if (act == 3) { x = fmaxf(x, 0.f); x = x * x; }
;                             v[n][e] = x;
;                         }
;                     }
;                     u32x4 w; w.x = cvt_pk_bf16(v[0][0], v[0][1]); w.y = cvt_pk_bf16(v[0][2], v[0][3]); w.z = cvt_pk_bf16(v[1][0], v[1][1]); w.w = cvt_pk_bf16(v[1][2], v[1][3]);
;                     *(u32x4*)(rowp + bj * HALF) = w;
	v_max_f32_e32 v82, 0, v82
	v_max_f32_e32 v83, 0, v83
	v_pk_mul_f32 v[84:85], v[84:85], v[84:85]
	v_pk_mul_f32 v[86:87], v[86:87], v[86:87]
	v_pk_mul_f32 v[80:81], v[80:81], v[80:81]
	v_pk_mul_f32 v[82:83], v[82:83], v[82:83]
	v_cvt_pk_bf16_f32 v84, v84, v85
	v_cvt_pk_bf16_f32 v85, v86, v87
	v_cvt_pk_bf16_f32 v86, v80, v81
	v_cvt_pk_bf16_f32 v87, v82, v83
	global_store_dwordx4 v[142:143], v[84:87], off offset:256
	v_lshl_add_u64 v[144:145], v[142:143], 0, s[0:1]
	v_pk_mul_f32 v[76:77], v[76:77], v[158:159] op_sel_hi:[1,0]
	v_pk_mul_f32 v[78:79], v[78:79], v[158:159] op_sel_hi:[1,0]
	v_pk_mul_f32 v[72:73], v[72:73], v[158:159] op_sel_hi:[1,0]
	v_pk_mul_f32 v[74:75], v[74:75], v[158:159] op_sel_hi:[1,0]
	v_max_f32_e32 v76, 0, v76
	v_max_f32_e32 v77, 0, v77
	v_max_f32_e32 v78, 0, v78
	v_max_f32_e32 v79, 0, v79
	v_max_f32_e32 v72, 0, v72
	v_max_f32_e32 v73, 0, v73
	v_max_f32_e32 v74, 0, v74
	v_max_f32_e32 v75, 0, v75
	v_pk_mul_f32 v[76:77], v[76:77], v[76:77]
	v_pk_mul_f32 v[78:79], v[78:79], v[78:79]
	v_pk_mul_f32 v[72:73], v[72:73], v[72:73]
	v_pk_mul_f32 v[74:75], v[74:75], v[74:75]
	v_cvt_pk_bf16_f32 v76, v76, v77
	v_cvt_pk_bf16_f32 v77, v78, v79
	v_cvt_pk_bf16_f32 v78, v72, v73
	v_cvt_pk_bf16_f32 v79, v74, v75
	global_store_dwordx4 v[144:145], v[76:79], off
	v_pk_mul_f32 v[68:69], v[68:69], v[158:159] op_sel_hi:[1,0]
	v_pk_mul_f32 v[70:71], v[70:71], v[158:159] op_sel_hi:[1,0]
	v_pk_mul_f32 v[64:65], v[64:65], v[158:159] op_sel_hi:[1,0]
	v_pk_mul_f32 v[66:67], v[66:67], v[158:159] op_sel_hi:[1,0]
	v_max_f32_e32 v68, 0, v68
	v_max_f32_e32 v69, 0, v69
	v_max_f32_e32 v70, 0, v70
	v_max_f32_e32 v71, 0, v71
	v_max_f32_e32 v64, 0, v64
	v_max_f32_e32 v65, 0, v65
	v_max_f32_e32 v66, 0, v66
	v_max_f32_e32 v67, 0, v67
	v_pk_mul_f32 v[68:69], v[68:69], v[68:69]
	v_pk_mul_f32 v[70:71], v[70:71], v[70:71]
	v_pk_mul_f32 v[64:65], v[64:65], v[64:65]
	v_pk_mul_f32 v[66:67], v[66:67], v[66:67]
	v_cvt_pk_bf16_f32 v68, v68, v69
	v_cvt_pk_bf16_f32 v69, v70, v71
	v_cvt_pk_bf16_f32 v70, v64, v65
	v_cvt_pk_bf16_f32 v71, v66, v67
	global_store_dwordx4 v[144:145], v[68:71], off offset:256
	v_lshl_add_u64 v[142:143], v[168:169], 0, 0
	v_pk_mul_f32 v[60:61], v[60:61], v[160:161] op_sel_hi:[1,0]
	v_pk_mul_f32 v[62:63], v[62:63], v[160:161] op_sel_hi:[1,0]
	v_pk_mul_f32 v[56:57], v[56:57], v[160:161] op_sel_hi:[1,0]
	v_pk_mul_f32 v[58:59], v[58:59], v[160:161] op_sel_hi:[1,0]
	v_max_f32_e32 v60, 0, v60
	v_max_f32_e32 v61, 0, v61
	v_max_f32_e32 v62, 0, v62
	v_max_f32_e32 v63, 0, v63
	v_max_f32_e32 v56, 0, v56
	v_max_f32_e32 v57, 0, v57
	v_max_f32_e32 v58, 0, v58
	v_max_f32_e32 v59, 0, v59
	v_pk_mul_f32 v[60:61], v[60:61], v[60:61]
	v_pk_mul_f32 v[62:63], v[62:63], v[62:63]
	v_pk_mul_f32 v[56:57], v[56:57], v[56:57]
	v_pk_mul_f32 v[58:59], v[58:59], v[58:59]
	v_cvt_pk_bf16_f32 v60, v60, v61
	v_cvt_pk_bf16_f32 v61, v62, v63
	v_cvt_pk_bf16_f32 v62, v56, v57
	v_cvt_pk_bf16_f32 v63, v58, v59
	global_store_dwordx4 v[142:143], v[60:63], off
	v_pk_mul_f32 v[52:53], v[52:53], v[160:161] op_sel_hi:[1,0]
	v_pk_mul_f32 v[54:55], v[54:55], v[160:161] op_sel_hi:[1,0]
	v_pk_mul_f32 v[48:49], v[48:49], v[160:161] op_sel_hi:[1,0]
	v_pk_mul_f32 v[50:51], v[50:51], v[160:161] op_sel_hi:[1,0]
	v_max_f32_e32 v52, 0, v52
	v_max_f32_e32 v53, 0, v53
	v_max_f32_e32 v54, 0, v54
	v_max_f32_e32 v55, 0, v55
	v_max_f32_e32 v48, 0, v48
	v_max_f32_e32 v49, 0, v49
	v_max_f32_e32 v50, 0, v50
	v_max_f32_e32 v51, 0, v51
	v_pk_mul_f32 v[52:53], v[52:53], v[52:53]
	v_pk_mul_f32 v[54:55], v[54:55], v[54:55]
	v_pk_mul_f32 v[48:49], v[48:49], v[48:49]
	v_pk_mul_f32 v[50:51], v[50:51], v[50:51]
	v_cvt_pk_bf16_f32 v52, v52, v53
	v_cvt_pk_bf16_f32 v53, v54, v55
	v_cvt_pk_bf16_f32 v54, v48, v49
	v_cvt_pk_bf16_f32 v55, v50, v51
	global_store_dwordx4 v[142:143], v[52:55], off offset:256
	v_lshl_add_u64 v[144:145], v[142:143], 0, s[0:1]
	v_pk_mul_f32 v[44:45], v[44:45], v[162:163] op_sel_hi:[1,0]
	v_pk_mul_f32 v[46:47], v[46:47], v[162:163] op_sel_hi:[1,0]
	v_pk_mul_f32 v[40:41], v[40:41], v[162:163] op_sel_hi:[1,0]
	v_pk_mul_f32 v[42:43], v[42:43], v[162:163] op_sel_hi:[1,0]
	v_max_f32_e32 v44, 0, v44
	v_max_f32_e32 v45, 0, v45
	v_max_f32_e32 v46, 0, v46
	v_max_f32_e32 v47, 0, v47
	v_max_f32_e32 v40, 0, v40
	v_max_f32_e32 v41, 0, v41
	v_max_f32_e32 v42, 0, v42
	v_max_f32_e32 v43, 0, v43
	v_pk_mul_f32 v[44:45], v[44:45], v[44:45]
	v_pk_mul_f32 v[46:47], v[46:47], v[46:47]
	v_pk_mul_f32 v[40:41], v[40:41], v[40:41]
	v_pk_mul_f32 v[42:43], v[42:43], v[42:43]
; __device__ __forceinline__ unsigned cvt_pk_bf16(float lo, float hi) { unsigned r; asm volatile("v_cvt_pk_bf16_f32 %0, %1, %2" : "=v"(r) : "v"(lo), "v"(hi)); return r; }
; __device__ __forceinline__ float silu_f(float v) { return v * __builtin_amdgcn_rcpf(1.f + __expf(-v)); }
; #define PG8_BAR __builtin_amdgcn_s_barrier()
;     __device__ __forceinline__ void operator()(const f32x4 (&acc)[2][2][4][2], const Unit& u, int wr, int wc, int fr, int fq, int ui, PG8_LAS unsigned char* lds) const {
;     ...
;                     f32x4 v[2] = {acc[ai][bj][m][0] * rs, acc[ai][bj][m][1] * rs};
;                     if (ksum) { csum[bj][0] += v[0]; csum[bj][1] += v[1]; }
; #pragma unroll
;                     for (int n = 0; n < 2; ++n) {
;                         f32x4 lbv = (f32x4){0.f, 0.f, 0.f, 0.f};
;                         if (act == 2) lbv = *(const f32x4*)(lb + (col0 - 1024) + bj * HALF + 4 * n);
; #pragma unroll
;                         for (int e = 0; e < 4; ++e) {
;                             float x = v[n][e];
;                             if (act == 1) x = silu_f(x);
;                             else if (act == 2) { const float l = lbv[e]; x = __logf(l + (1.f - l) * __builtin_amdgcn_rcpf(1.f + __expf(-x))); }
;                             else if (act == 3) { x = fmaxf(x, 0.f); x = x * x; }
;                             v[n][e] = x;
;                         }
;                     }
;                     u32x4 w; w.x = cvt_pk_bf16(v[0][0], v[0][1]); w.y = cvt_pk_bf16(v[0][2], v[0][3]); w.z = cvt_pk_bf16(v[1][0], v[1][1]); w.w = cvt_pk_bf16(v[1][2], v[1][3]);
;                     *(u32x4*)(rowp + bj * HALF) = w;
; template <class Epi, class Sched, bool ALIGN_EPI = false, bool SP2 = false>
; __device__ __forceinline__ void gemm_phase(PG8_LAS unsigned char* lds, const Gemm g, const Sched& S, const Epi& E) {
;     ...
;         if (!has_next) break;
; #pragma unroll
;         for (int a = 0; a < 2; ++a)
; #pragma unroll
;             for (int b = 0; b < 2; ++b)
; #pragma unroll
;                 for (int m = 0; m < 4; ++m)
; #pragma unroll
;                     for (int n = 0; n < 2; ++n) acc[a][b][m][n] = (f32x4){0.f, 0.f, 0.f, 0.f};
;         cur = nxt; cA = nA; cB = nB; ++ui;
;         if constexpr (ALIGN_EPI) { if (wr == 1) PG8_BAR; }
	v_cvt_pk_bf16_f32 v44, v44, v45
	v_cvt_pk_bf16_f32 v45, v46, v47
	v_cvt_pk_bf16_f32 v46, v40, v41
	v_cvt_pk_bf16_f32 v47, v42, v43
	global_store_dwordx4 v[144:145], v[44:47], off
	v_pk_mul_f32 v[36:37], v[36:37], v[162:163] op_sel_hi:[1,0]
	v_pk_mul_f32 v[38:39], v[38:39], v[162:163] op_sel_hi:[1,0]
	v_pk_mul_f32 v[32:33], v[32:33], v[162:163] op_sel_hi:[1,0]
	v_pk_mul_f32 v[34:35], v[34:35], v[162:163] op_sel_hi:[1,0]
	v_max_f32_e32 v36, 0, v36
	v_max_f32_e32 v37, 0, v37
	v_max_f32_e32 v38, 0, v38
	v_max_f32_e32 v39, 0, v39
	v_max_f32_e32 v32, 0, v32
	v_max_f32_e32 v33, 0, v33
	v_max_f32_e32 v34, 0, v34
	v_max_f32_e32 v35, 0, v35
	v_pk_mul_f32 v[36:37], v[36:37], v[36:37]
	v_pk_mul_f32 v[38:39], v[38:39], v[38:39]
	v_pk_mul_f32 v[32:33], v[32:33], v[32:33]
	v_pk_mul_f32 v[34:35], v[34:35], v[34:35]
	v_cvt_pk_bf16_f32 v36, v36, v37
	v_cvt_pk_bf16_f32 v37, v38, v39
	v_cvt_pk_bf16_f32 v38, v32, v33
	v_cvt_pk_bf16_f32 v39, v34, v35
	global_store_dwordx4 v[144:145], v[36:39], off offset:256
	v_lshl_add_u64 v[142:143], v[144:145], 0, s[0:1]
	v_pk_mul_f32 v[28:29], v[28:29], v[164:165] op_sel_hi:[1,0]
	v_pk_mul_f32 v[30:31], v[30:31], v[164:165] op_sel_hi:[1,0]
	v_pk_mul_f32 v[24:25], v[24:25], v[164:165] op_sel_hi:[1,0]
	v_pk_mul_f32 v[26:27], v[26:27], v[164:165] op_sel_hi:[1,0]
	v_max_f32_e32 v28, 0, v28
	v_max_f32_e32 v29, 0, v29
	v_max_f32_e32 v30, 0, v30
	v_max_f32_e32 v31, 0, v31
	v_max_f32_e32 v24, 0, v24
	v_max_f32_e32 v25, 0, v25
	v_max_f32_e32 v26, 0, v26
	v_max_f32_e32 v27, 0, v27
	v_pk_mul_f32 v[28:29], v[28:29], v[28:29]
	v_pk_mul_f32 v[30:31], v[30:31], v[30:31]
	v_pk_mul_f32 v[24:25], v[24:25], v[24:25]
	v_pk_mul_f32 v[26:27], v[26:27], v[26:27]
	v_cvt_pk_bf16_f32 v28, v28, v29
	v_cvt_pk_bf16_f32 v29, v30, v31
	v_cvt_pk_bf16_f32 v30, v24, v25
	v_cvt_pk_bf16_f32 v31, v26, v27
	global_store_dwordx4 v[142:143], v[28:31], off
	v_pk_mul_f32 v[20:21], v[20:21], v[164:165] op_sel_hi:[1,0]
	v_pk_mul_f32 v[22:23], v[22:23], v[164:165] op_sel_hi:[1,0]
	v_pk_mul_f32 v[16:17], v[16:17], v[164:165] op_sel_hi:[1,0]
	v_pk_mul_f32 v[18:19], v[18:19], v[164:165] op_sel_hi:[1,0]
	v_max_f32_e32 v20, 0, v20
	v_max_f32_e32 v21, 0, v21
	v_max_f32_e32 v22, 0, v22
	v_max_f32_e32 v23, 0, v23
	v_max_f32_e32 v16, 0, v16
	v_max_f32_e32 v17, 0, v17
	v_max_f32_e32 v18, 0, v18
	v_max_f32_e32 v19, 0, v19
	v_pk_mul_f32 v[20:21], v[20:21], v[20:21]
	v_pk_mul_f32 v[22:23], v[22:23], v[22:23]
	v_pk_mul_f32 v[16:17], v[16:17], v[16:17]
	v_pk_mul_f32 v[18:19], v[18:19], v[18:19]
	v_cvt_pk_bf16_f32 v20, v20, v21
	v_cvt_pk_bf16_f32 v21, v22, v23
	v_cvt_pk_bf16_f32 v22, v16, v17
	v_cvt_pk_bf16_f32 v23, v18, v19
	global_store_dwordx4 v[142:143], v[20:23], off offset:256
	v_lshl_add_u64 v[144:145], v[142:143], 0, s[0:1]
	v_pk_mul_f32 v[12:13], v[12:13], v[166:167] op_sel_hi:[1,0]
	v_pk_mul_f32 v[14:15], v[14:15], v[166:167] op_sel_hi:[1,0]
	v_pk_mul_f32 v[8:9], v[8:9], v[166:167] op_sel_hi:[1,0]
	v_pk_mul_f32 v[10:11], v[10:11], v[166:167] op_sel_hi:[1,0]
	v_max_f32_e32 v12, 0, v12
	v_max_f32_e32 v13, 0, v13
	v_max_f32_e32 v14, 0, v14
	v_max_f32_e32 v15, 0, v15
	v_max_f32_e32 v8, 0, v8
	v_max_f32_e32 v9, 0, v9
	v_max_f32_e32 v10, 0, v10
	v_max_f32_e32 v11, 0, v11
	v_pk_mul_f32 v[12:13], v[12:13], v[12:13]
	v_pk_mul_f32 v[14:15], v[14:15], v[14:15]
	v_pk_mul_f32 v[8:9], v[8:9], v[8:9]
	v_pk_mul_f32 v[10:11], v[10:11], v[10:11]
	v_cvt_pk_bf16_f32 v12, v12, v13
	v_cvt_pk_bf16_f32 v13, v14, v15
	v_cvt_pk_bf16_f32 v14, v8, v9
	v_cvt_pk_bf16_f32 v15, v10, v11
	global_store_dwordx4 v[144:145], v[12:15], off
	v_pk_mul_f32 v[4:5], v[4:5], v[166:167] op_sel_hi:[1,0]
	v_pk_mul_f32 v[6:7], v[6:7], v[166:167] op_sel_hi:[1,0]
	v_pk_mul_f32 v[0:1], v[0:1], v[166:167] op_sel_hi:[1,0]
	v_pk_mul_f32 v[2:3], v[2:3], v[166:167] op_sel_hi:[1,0]
	v_max_f32_e32 v4, 0, v4
	v_max_f32_e32 v5, 0, v5
	v_max_f32_e32 v6, 0, v6
	v_max_f32_e32 v7, 0, v7
	v_max_f32_e32 v0, 0, v0
	v_max_f32_e32 v1, 0, v1
	v_max_f32_e32 v2, 0, v2
	v_max_f32_e32 v3, 0, v3
	v_pk_mul_f32 v[4:5], v[4:5], v[4:5]
	v_pk_mul_f32 v[6:7], v[6:7], v[6:7]
	v_pk_mul_f32 v[0:1], v[0:1], v[0:1]
	v_pk_mul_f32 v[2:3], v[2:3], v[2:3]
	v_cvt_pk_bf16_f32 v4, v4, v5
	v_cvt_pk_bf16_f32 v5, v6, v7
	v_cvt_pk_bf16_f32 v6, v0, v1
	v_cvt_pk_bf16_f32 v7, v2, v3
	global_store_dwordx4 v[144:145], v[4:7], off offset:256
	s_andn2_b64 vcc, exec, s[42:43]
	s_mov_b64 s[0:1], -1
	s_cbranch_vccnz .LBB0_1744
	s_andn2_b64 vcc, exec, s[44:45]
	s_cbranch_vccnz .LBB0_1743
	s_barrier
	s_branch .LBB0_1743
